# P0: nt input loads plus write-through (sc1) output stores
# speedup vs baseline: 1.0428x; 1.0008x over previous
; #define LAS __attribute__((address_space(3)))
; __device__ __forceinline__ unsigned pk_bf16(float lo, float hi) { typedef __bf16 b2 __attribute__((ext_vector_type(2))); f32x2 v = {lo, hi}; b2 b = __builtin_convertvector(v, b2); return __builtin_bit_cast(unsigned, b); }
; template <bool MAP> __device__ __forceinline__ void p0_transpose_item(const float* W, int K, int N, u16* WT, LAS float* scr, int item, int lane) {
;     const int nblk = N / 32, kb = item / nblk, nb = item % nblk, k0 = 64 * kb, n0 = 32 * nb;
;     float tv[32];
; #pragma unroll
;     for (int i = 0; i < 32; ++i) tv[i] = W[(size_t)(k0 + 2 * i + (lane >> 5)) * N + n0 + (lane & 31)];
; #pragma unroll
;     for (int i = 0; i < 32; ++i) scr[(2 * i + (lane >> 5)) * 33 + (lane & 31)] = tv[i];
;     asm volatile("s_waitcnt lgkmcnt(0)" ::: "memory");
;     const int c = lane & 7;
; #pragma unroll
;     for (int j = 0; j < 4; ++j) { const int n = (lane >> 3) + 8 * j; const LAS float* s = scr + (8 * c) * 33 + n;
;         u32x4 o; o.x = pk_bf16(s[0 * 33], s[1 * 33]); o.y = pk_bf16(s[2 * 33], s[3 * 33]); o.z = pk_bf16(s[4 * 33], s[5 * 33]); o.w = pk_bf16(s[6 * 33], s[7 * 33]);
;         const int r = MAP ? wt_row_of_col(n0 + n) : (n0 + n);
;         *(u32x4*)(WT + (size_t)r * K + k0 + 8 * c) = o; }
; __device__ __forceinline__ void p0_prologue(const Ptrs& P, LAS unsigned char* lds, int vcu, int G) {
;     ...
;     for (int it = gw; it < NITEMS; it += NGW) {
;         int r = it;
;         if (r < I_IN) { p0_transpose_item<true>(P.w_in, 1024, NIN, (u16*)(P.ws + WS_WT), scr, r, lane); continue; } r -= I_IN;
;         if (r < I_A) { p0_transpose_item<false>(P.wa, 1024, 1024, (u16*)(P.ws + WS_WA), scr, r, lane); continue; } r -= I_A;
;         if (r < I_B) { p0_transpose_item<false>(P.wb, 512, 1024, (u16*)(P.ws + WS_WB), scr, r, lane); continue; } r -= I_B;
;         p0_transpose_item<false>(P.wo, 1024, 1024, (u16*)(P.ws + WS_WO), scr, r, lane);
.LBB0_24:
	s_cmpk_gt_i32 s28, 0x15ff
	s_mov_b64 s[8:9], -1
	s_cbranch_scc0 .LBB0_34
	s_cmpk_gt_u32 s28, 0x17ff
	s_cbranch_scc0 .LBB0_31
	s_cmpk_gt_u32 s28, 0x18ff
	s_cbranch_scc0 .LBB0_28
	s_add_i32 s8, s18, 0xfffce000
	s_and_b32 s8, s8, 0x3e0
	s_and_b32 s9, s21, 0xf0000
	s_or_b32 s9, s9, s8
	v_or_b32_e32 v0, s9, v26
	v_or_b32_e32 v14, s9, v29
	v_or_b32_e32 v15, s9, v30
	v_or_b32_e32 v16, s9, v31
	v_or_b32_e32 v17, s9, v32
	v_or_b32_e32 v18, s9, v33
	v_lshlrev_b32_e32 v0, 2, v0
	v_or_b32_e32 v12, s9, v27
	v_or_b32_e32 v13, s9, v28
	v_lshlrev_b32_e32 v14, 2, v14
	v_lshlrev_b32_e32 v15, 2, v15
	v_lshlrev_b32_e32 v16, 2, v16
	v_lshlrev_b32_e32 v17, 2, v17
	v_lshlrev_b32_e32 v18, 2, v18
	v_lshlrev_b32_e32 v12, 2, v12
	v_lshlrev_b32_e32 v13, 2, v13
	global_load_dword v19, v0, s[72:73] nt
	global_load_dword v20, v12, s[72:73] nt
	global_load_dword v21, v13, s[72:73] nt
	s_nop 0
	global_load_dword v14, v14, s[72:73] nt
	s_nop 0
	global_load_dword v15, v15, s[72:73] nt
	s_nop 0
	global_load_dword v16, v16, s[72:73] nt
	s_nop 0
	global_load_dword v17, v17, s[72:73] nt
	s_nop 0
	global_load_dword v18, v18, s[72:73] nt
	v_or_b32_e32 v0, s9, v34
	v_or_b32_e32 v22, s9, v37
	v_or_b32_e32 v23, s9, v38
	v_or_b32_e32 v71, s9, v39
	v_or_b32_e32 v72, s9, v40
	v_or_b32_e32 v73, s9, v41
	v_lshlrev_b32_e32 v0, 2, v0
	v_or_b32_e32 v12, s9, v35
	v_or_b32_e32 v13, s9, v36
	v_lshlrev_b32_e32 v22, 2, v22
	v_lshlrev_b32_e32 v23, 2, v23
	v_lshlrev_b32_e32 v71, 2, v71
	v_lshlrev_b32_e32 v72, 2, v72
	v_lshlrev_b32_e32 v73, 2, v73
	v_lshlrev_b32_e32 v12, 2, v12
	v_lshlrev_b32_e32 v13, 2, v13
	global_load_dword v74, v0, s[72:73] nt
	global_load_dword v75, v12, s[72:73] nt
	global_load_dword v76, v13, s[72:73] nt
	s_nop 0
	global_load_dword v22, v22, s[72:73] nt
	s_nop 0
	global_load_dword v23, v23, s[72:73] nt
	s_nop 0
	global_load_dword v71, v71, s[72:73] nt
	s_nop 0
	global_load_dword v72, v72, s[72:73] nt
	s_nop 0
	global_load_dword v73, v73, s[72:73] nt
	v_or_b32_e32 v0, s9, v42
	v_or_b32_e32 v77, s9, v45
	v_or_b32_e32 v78, s9, v46
	v_or_b32_e32 v79, s9, v47
	v_or_b32_e32 v80, s9, v48
	v_or_b32_e32 v81, s9, v49
	v_lshlrev_b32_e32 v0, 2, v0
	v_or_b32_e32 v12, s9, v43
	v_or_b32_e32 v13, s9, v44
	v_lshlrev_b32_e32 v77, 2, v77
	v_lshlrev_b32_e32 v78, 2, v78
	v_lshlrev_b32_e32 v79, 2, v79
	v_lshlrev_b32_e32 v80, 2, v80
	v_lshlrev_b32_e32 v81, 2, v81
	v_lshlrev_b32_e32 v12, 2, v12
	v_lshlrev_b32_e32 v13, 2, v13
	global_load_dword v82, v0, s[72:73] nt
	global_load_dword v83, v12, s[72:73] nt
	global_load_dword v84, v13, s[72:73] nt
	s_nop 0
	global_load_dword v77, v77, s[72:73] nt
	s_nop 0
	global_load_dword v78, v78, s[72:73] nt
	s_nop 0
	global_load_dword v79, v79, s[72:73] nt
	s_nop 0
	global_load_dword v80, v80, s[72:73] nt
	s_nop 0
	global_load_dword v81, v81, s[72:73] nt
	v_or_b32_e32 v0, s9, v50
	v_lshlrev_b32_e32 v85, 2, v0
	v_or_b32_e32 v0, s9, v51
	v_lshlrev_b32_e32 v86, 2, v0
	v_or_b32_e32 v0, s9, v52
	v_lshlrev_b32_e32 v87, 2, v0
	v_or_b32_e32 v0, s9, v53
	v_lshlrev_b32_e32 v88, 2, v0
	v_or_b32_e32 v0, s9, v54
	s_and_b32 s6, s20, 0x3e0
	v_lshlrev_b32_e32 v89, 2, v0
	v_or_b32_e32 v0, s9, v55
	v_lshlrev_b32_e32 v90, 2, v0
	v_or_b32_e32 v0, s9, v56
	s_add_i32 s6, s6, s21
	v_lshlrev_b32_e32 v91, 2, v0
	v_add_u32_e32 v0, s6, v26
	v_or_b32_e32 v0, 0xf800, v0
	v_lshl_add_u64 v[12:13], v[0:1], 2, s[72:73]
	global_load_dword v0, v85, s[72:73] nt
	s_nop 0
	global_load_dword v85, v86, s[72:73] nt
	s_nop 0
	global_load_dword v86, v87, s[72:73] nt
	s_nop 0
	global_load_dword v87, v88, s[72:73] nt
	s_nop 0
	global_load_dword v88, v89, s[72:73] nt
	s_nop 0
	global_load_dword v89, v90, s[72:73] nt
	s_nop 0
	global_load_dword v90, v91, s[72:73] nt
	s_nop 0
	global_load_dword v12, v[12:13], off nt
	s_and_b32 s6, s23, 0x3c0
	s_lshl_b32 s6, s6, 1
	s_waitcnt vmcnt(30)
	ds_write2_b32 v62, v19, v20 offset1:66
	s_waitcnt vmcnt(28)
	ds_write2_b32 v62, v21, v14 offset0:132 offset1:198
	s_waitcnt vmcnt(26)
	ds_write2_b32 v64, v15, v16 offset0:8 offset1:74
	s_waitcnt vmcnt(24)
	ds_write2_b32 v64, v17, v18 offset0:140 offset1:206
	s_waitcnt vmcnt(22)
	ds_write2_b32 v65, v74, v75 offset0:16 offset1:82
	s_waitcnt vmcnt(20)
	ds_write2_b32 v65, v76, v22 offset0:148 offset1:214
	s_waitcnt vmcnt(18)
	ds_write2_b32 v66, v23, v71 offset0:24 offset1:90
	s_waitcnt vmcnt(16)
	ds_write2_b32 v66, v72, v73 offset0:156 offset1:222
	s_waitcnt vmcnt(14)
	ds_write2_b32 v67, v82, v83 offset0:32 offset1:98
	s_waitcnt vmcnt(12)
	ds_write2_b32 v67, v84, v77 offset0:164 offset1:230
	s_waitcnt vmcnt(10)
	ds_write2_b32 v68, v78, v79 offset0:40 offset1:106
	s_waitcnt vmcnt(8)
	ds_write2_b32 v68, v80, v81 offset0:172 offset1:238
	s_waitcnt vmcnt(6)
	ds_write2_b32 v69, v0, v85 offset0:48 offset1:114
	s_waitcnt vmcnt(4)
	ds_write2_b32 v69, v86, v87 offset0:180 offset1:246
	s_waitcnt vmcnt(2)
	ds_write2_b32 v70, v88, v89 offset0:56 offset1:122
	s_waitcnt vmcnt(0)
	ds_write2_b32 v70, v90, v12 offset0:188 offset1:254
	s_waitcnt lgkmcnt(0)
	ds_read2_b32 v[16:17], v63 offset0:33 offset1:41
	ds_read2_b32 v[18:19], v63 offset1:8
	ds_read2_b32 v[20:21], v63 offset0:66 offset1:74
	ds_read2_b32 v[22:23], v63 offset0:99 offset1:107
	ds_read2_b32 v[72:73], v63 offset0:132 offset1:140
	ds_read2_b32 v[74:75], v63 offset0:165 offset1:173
	ds_read2_b32 v[76:77], v63 offset0:198 offset1:206
	ds_read2_b32 v[78:79], v63 offset0:231 offset1:239
	v_or_b32_e32 v0, s8, v58
	v_lshl_add_u64 v[80:81], v[6:7], 0, s[6:7]
	v_lshlrev_b32_e32 v0, 11, v0
	s_waitcnt lgkmcnt(6)
	v_cvt_pk_bf16_f32 v12, v18, v16
	s_waitcnt lgkmcnt(4)
	v_cvt_pk_bf16_f32 v13, v20, v22
	s_waitcnt lgkmcnt(2)
	v_cvt_pk_bf16_f32 v14, v72, v74
	s_waitcnt lgkmcnt(0)
; #define LAS __attribute__((address_space(3)))
; __device__ __forceinline__ unsigned pk_bf16(float lo, float hi) { typedef __bf16 b2 __attribute__((ext_vector_type(2))); f32x2 v = {lo, hi}; b2 b = __builtin_convertvector(v, b2); return __builtin_bit_cast(unsigned, b); }
; template <bool MAP> __device__ __forceinline__ void p0_transpose_item(const float* W, int K, int N, u16* WT, LAS float* scr, int item, int lane) {
;     ...
;     for (int j = 0; j < 4; ++j) { const int n = (lane >> 3) + 8 * j; const LAS float* s = scr + (8 * c) * 33 + n;
;         u32x4 o; o.x = pk_bf16(s[0 * 33], s[1 * 33]); o.y = pk_bf16(s[2 * 33], s[3 * 33]); o.z = pk_bf16(s[4 * 33], s[5 * 33]); o.w = pk_bf16(s[6 * 33], s[7 * 33]);
;         const int r = MAP ? wt_row_of_col(n0 + n) : (n0 + n);
;         *(u32x4*)(WT + (size_t)r * K + k0 + 8 * c) = o; }
	v_cvt_pk_bf16_f32 v15, v76, v78
	v_lshl_add_u64 v[82:83], v[80:81], 0, v[0:1]
	global_store_dwordx4 v[82:83], v[12:15], off sc1
	v_or_b32_e32 v0, s8, v59
	v_lshlrev_b32_e32 v0, 11, v0
	v_cvt_pk_bf16_f32 v12, v19, v17
	v_cvt_pk_bf16_f32 v13, v21, v23
	v_cvt_pk_bf16_f32 v14, v73, v75
	v_cvt_pk_bf16_f32 v15, v77, v79
	ds_read2_b32 v[18:19], v63 offset0:49 offset1:57
	ds_read2_b32 v[20:21], v63 offset0:16 offset1:24
	ds_read2_b32 v[22:23], v63 offset0:82 offset1:90
	ds_read2_b32 v[72:73], v63 offset0:115 offset1:123
	ds_read2_b32 v[74:75], v63 offset0:148 offset1:156
	ds_read2_b32 v[76:77], v63 offset0:181 offset1:189
	ds_read2_b32 v[78:79], v63 offset0:214 offset1:222
	ds_read2_b32 v[82:83], v63 offset0:247 offset1:255
	v_lshl_add_u64 v[16:17], v[80:81], 0, v[0:1]
	v_or_b32_e32 v0, s8, v60
	v_lshlrev_b32_e32 v0, 11, v0
	global_store_dwordx4 v[16:17], v[12:15], off sc1
	v_lshl_add_u64 v[16:17], v[80:81], 0, v[0:1]
	v_or_b32_e32 v0, s8, v61
	s_waitcnt lgkmcnt(6)
	v_cvt_pk_bf16_f32 v12, v20, v18
	s_waitcnt lgkmcnt(4)
	v_cvt_pk_bf16_f32 v13, v22, v72
	s_waitcnt lgkmcnt(2)
	v_cvt_pk_bf16_f32 v14, v74, v76
	s_waitcnt lgkmcnt(0)
	v_cvt_pk_bf16_f32 v15, v78, v82
	v_lshlrev_b32_e32 v0, 11, v0
	global_store_dwordx4 v[16:17], v[12:15], off sc1
	v_lshl_add_u64 v[16:17], v[80:81], 0, v[0:1]
	s_mov_b64 s[8:9], 0
	v_cvt_pk_bf16_f32 v12, v21, v19
	v_cvt_pk_bf16_f32 v13, v23, v73
	v_cvt_pk_bf16_f32 v14, v75, v77
	v_cvt_pk_bf16_f32 v15, v79, v83
	global_store_dwordx4 v[16:17], v[12:15], off sc1
	s_waitcnt lgkmcnt(0)
.LBB0_28:
	s_andn2_b64 vcc, exec, s[8:9]
	s_cbranch_vccnz .LBB0_30
; #define LAS __attribute__((address_space(3)))
; __device__ __forceinline__ unsigned pk_bf16(float lo, float hi) { typedef __bf16 b2 __attribute__((ext_vector_type(2))); f32x2 v = {lo, hi}; b2 b = __builtin_convertvector(v, b2); return __builtin_bit_cast(unsigned, b); }
; template <bool MAP> __device__ __forceinline__ void p0_transpose_item(const float* W, int K, int N, u16* WT, LAS float* scr, int item, int lane) {
;     const int nblk = N / 32, kb = item / nblk, nb = item % nblk, k0 = 64 * kb, n0 = 32 * nb;
;     float tv[32];
; #pragma unroll
;     for (int i = 0; i < 32; ++i) tv[i] = W[(size_t)(k0 + 2 * i + (lane >> 5)) * N + n0 + (lane & 31)];
; #pragma unroll
;     for (int i = 0; i < 32; ++i) scr[(2 * i + (lane >> 5)) * 33 + (lane & 31)] = tv[i];
;     asm volatile("s_waitcnt lgkmcnt(0)" ::: "memory");
;     const int c = lane & 7;
; #pragma unroll
;     for (int j = 0; j < 4; ++j) { const int n = (lane >> 3) + 8 * j; const LAS float* s = scr + (8 * c) * 33 + n;
;         u32x4 o; o.x = pk_bf16(s[0 * 33], s[1 * 33]); o.y = pk_bf16(s[2 * 33], s[3 * 33]); o.z = pk_bf16(s[4 * 33], s[5 * 33]); o.w = pk_bf16(s[6 * 33], s[7 * 33]);
;         const int r = MAP ? wt_row_of_col(n0 + n) : (n0 + n);
;         *(u32x4*)(WT + (size_t)r * K + k0 + 8 * c) = o; }
;     asm volatile("s_waitcnt lgkmcnt(0)" ::: "memory");
	s_add_i32 s8, s18, 0xfffd0000
	s_add_i32 s9, s21, 0xc80000
	s_and_b32 s8, s8, 0x3e0
	s_and_b32 s9, s9, 0xf0000
	s_or_b32 s9, s8, s9
	v_or_b32_e32 v0, s9, v26
	v_or_b32_e32 v14, s9, v29
	v_or_b32_e32 v15, s9, v30
	v_or_b32_e32 v16, s9, v31
	v_or_b32_e32 v17, s9, v32
	v_or_b32_e32 v18, s9, v33
	v_lshlrev_b32_e32 v0, 2, v0
	v_or_b32_e32 v12, s9, v27
	v_or_b32_e32 v13, s9, v28
	v_lshlrev_b32_e32 v14, 2, v14
	v_lshlrev_b32_e32 v15, 2, v15
	v_lshlrev_b32_e32 v16, 2, v16
	v_lshlrev_b32_e32 v17, 2, v17
	v_lshlrev_b32_e32 v18, 2, v18
	v_lshlrev_b32_e32 v12, 2, v12
	v_lshlrev_b32_e32 v13, 2, v13
	global_load_dword v19, v0, s[70:71] nt
	global_load_dword v20, v12, s[70:71] nt
	global_load_dword v21, v13, s[70:71] nt
	s_nop 0
	global_load_dword v14, v14, s[70:71] nt
	s_nop 0
	global_load_dword v15, v15, s[70:71] nt
	s_nop 0
	global_load_dword v16, v16, s[70:71] nt
	s_nop 0
	global_load_dword v17, v17, s[70:71] nt
	s_nop 0
	global_load_dword v18, v18, s[70:71] nt
	v_or_b32_e32 v0, s9, v34
	v_or_b32_e32 v22, s9, v37
	v_or_b32_e32 v23, s9, v38
	v_or_b32_e32 v71, s9, v39
	v_or_b32_e32 v72, s9, v40
	v_or_b32_e32 v73, s9, v41
	v_lshlrev_b32_e32 v0, 2, v0
	v_or_b32_e32 v12, s9, v35
	v_or_b32_e32 v13, s9, v36
	v_lshlrev_b32_e32 v22, 2, v22
	v_lshlrev_b32_e32 v23, 2, v23
	v_lshlrev_b32_e32 v71, 2, v71
	v_lshlrev_b32_e32 v72, 2, v72
	v_lshlrev_b32_e32 v73, 2, v73
	v_lshlrev_b32_e32 v12, 2, v12
	v_lshlrev_b32_e32 v13, 2, v13
	global_load_dword v74, v0, s[70:71] nt
	global_load_dword v75, v12, s[70:71] nt
	global_load_dword v76, v13, s[70:71] nt
	s_nop 0
	global_load_dword v22, v22, s[70:71] nt
	s_nop 0
	global_load_dword v23, v23, s[70:71] nt
	s_nop 0
	global_load_dword v71, v71, s[70:71] nt
	s_nop 0
	global_load_dword v72, v72, s[70:71] nt
	s_nop 0
	global_load_dword v73, v73, s[70:71] nt
	v_or_b32_e32 v0, s9, v42
	v_or_b32_e32 v77, s9, v45
	v_or_b32_e32 v78, s9, v46
	v_or_b32_e32 v79, s9, v47
	v_or_b32_e32 v80, s9, v48
	v_or_b32_e32 v81, s9, v49
	v_lshlrev_b32_e32 v0, 2, v0
	v_or_b32_e32 v12, s9, v43
	v_or_b32_e32 v13, s9, v44
	v_lshlrev_b32_e32 v77, 2, v77
	v_lshlrev_b32_e32 v78, 2, v78
	v_lshlrev_b32_e32 v79, 2, v79
	v_lshlrev_b32_e32 v80, 2, v80
	v_lshlrev_b32_e32 v81, 2, v81
	v_lshlrev_b32_e32 v12, 2, v12
	v_lshlrev_b32_e32 v13, 2, v13
	global_load_dword v82, v0, s[70:71] nt
	global_load_dword v83, v12, s[70:71] nt
	global_load_dword v84, v13, s[70:71] nt
	s_nop 0
	global_load_dword v77, v77, s[70:71] nt
	s_nop 0
	global_load_dword v78, v78, s[70:71] nt
	s_nop 0
	global_load_dword v79, v79, s[70:71] nt
	s_nop 0
	global_load_dword v80, v80, s[70:71] nt
	s_nop 0
	global_load_dword v81, v81, s[70:71] nt
	v_or_b32_e32 v0, s9, v50
	v_lshlrev_b32_e32 v85, 2, v0
	v_or_b32_e32 v0, s9, v51
	v_lshlrev_b32_e32 v86, 2, v0
	v_or_b32_e32 v0, s9, v52
	v_lshlrev_b32_e32 v87, 2, v0
	v_or_b32_e32 v0, s9, v53
	v_lshlrev_b32_e32 v88, 2, v0
	v_or_b32_e32 v0, s9, v54
	s_and_b32 s6, s25, 0x3e0
	v_lshlrev_b32_e32 v89, 2, v0
	v_or_b32_e32 v0, s9, v55
	v_lshlrev_b32_e32 v90, 2, v0
	v_or_b32_e32 v0, s9, v56
	s_add_i32 s6, s6, s21
	v_lshlrev_b32_e32 v91, 2, v0
	v_add_u32_e32 v0, s6, v26
	v_add_u32_e32 v0, 0x80000, v0
	v_or_b32_e32 v0, 0xf800, v0
	v_lshl_add_u64 v[12:13], v[0:1], 2, s[70:71]
	global_load_dword v0, v85, s[70:71] nt
	s_nop 0
	global_load_dword v85, v86, s[70:71] nt
	s_nop 0
	global_load_dword v86, v87, s[70:71] nt
	s_nop 0
	global_load_dword v87, v88, s[70:71] nt
	s_nop 0
	global_load_dword v88, v89, s[70:71] nt
	s_nop 0
	global_load_dword v89, v90, s[70:71] nt
	s_nop 0
	global_load_dword v90, v91, s[70:71] nt
	s_nop 0
	global_load_dword v12, v[12:13], off nt
	s_add_i32 s6, s23, 0x200
	s_and_b32 s6, s6, 0x3c0
	s_lshl_b32 s6, s6, 1
	s_waitcnt vmcnt(30)
	ds_write2_b32 v62, v19, v20 offset1:66
	s_waitcnt vmcnt(28)
	ds_write2_b32 v62, v21, v14 offset0:132 offset1:198
	s_waitcnt vmcnt(26)
	ds_write2_b32 v64, v15, v16 offset0:8 offset1:74
	s_waitcnt vmcnt(24)
	ds_write2_b32 v64, v17, v18 offset0:140 offset1:206
	s_waitcnt vmcnt(22)
	ds_write2_b32 v65, v74, v75 offset0:16 offset1:82
	s_waitcnt vmcnt(20)
	ds_write2_b32 v65, v76, v22 offset0:148 offset1:214
	s_waitcnt vmcnt(18)
	ds_write2_b32 v66, v23, v71 offset0:24 offset1:90
	s_waitcnt vmcnt(16)
	ds_write2_b32 v66, v72, v73 offset0:156 offset1:222
	s_waitcnt vmcnt(14)
	ds_write2_b32 v67, v82, v83 offset0:32 offset1:98
	s_waitcnt vmcnt(12)
	ds_write2_b32 v67, v84, v77 offset0:164 offset1:230
	s_waitcnt vmcnt(10)
	ds_write2_b32 v68, v78, v79 offset0:40 offset1:106
	s_waitcnt vmcnt(8)
	ds_write2_b32 v68, v80, v81 offset0:172 offset1:238
	s_waitcnt vmcnt(6)
	ds_write2_b32 v69, v0, v85 offset0:48 offset1:114
	s_waitcnt vmcnt(4)
	ds_write2_b32 v69, v86, v87 offset0:180 offset1:246
	s_waitcnt vmcnt(2)
	ds_write2_b32 v70, v88, v89 offset0:56 offset1:122
	s_waitcnt vmcnt(0)
	ds_write2_b32 v70, v90, v12 offset0:188 offset1:254
	s_waitcnt lgkmcnt(0)
	ds_read2_b32 v[16:17], v63 offset0:33 offset1:41
	ds_read2_b32 v[18:19], v63 offset1:8
	ds_read2_b32 v[20:21], v63 offset0:66 offset1:74
	ds_read2_b32 v[22:23], v63 offset0:99 offset1:107
	ds_read2_b32 v[72:73], v63 offset0:132 offset1:140
	ds_read2_b32 v[74:75], v63 offset0:165 offset1:173
	ds_read2_b32 v[76:77], v63 offset0:198 offset1:206
	ds_read2_b32 v[78:79], v63 offset0:231 offset1:239
	v_or_b32_e32 v0, s8, v58
	v_lshl_add_u64 v[80:81], v[8:9], 0, s[6:7]
	v_lshlrev_b32_e32 v0, 10, v0
	s_waitcnt lgkmcnt(6)
	v_cvt_pk_bf16_f32 v12, v18, v16
	s_waitcnt lgkmcnt(4)
	v_cvt_pk_bf16_f32 v13, v20, v22
	s_waitcnt lgkmcnt(2)
	v_cvt_pk_bf16_f32 v14, v72, v74
	s_waitcnt lgkmcnt(0)
	v_cvt_pk_bf16_f32 v15, v76, v78
	v_lshl_add_u64 v[82:83], v[80:81], 0, v[0:1]
	global_store_dwordx4 v[82:83], v[12:15], off sc1
	v_or_b32_e32 v0, s8, v59
	v_lshlrev_b32_e32 v0, 10, v0
	v_cvt_pk_bf16_f32 v12, v19, v17
	v_cvt_pk_bf16_f32 v13, v21, v23
	v_cvt_pk_bf16_f32 v14, v73, v75
	v_cvt_pk_bf16_f32 v15, v77, v79
	ds_read2_b32 v[18:19], v63 offset0:49 offset1:57
	ds_read2_b32 v[20:21], v63 offset0:16 offset1:24
	ds_read2_b32 v[22:23], v63 offset0:82 offset1:90
	ds_read2_b32 v[72:73], v63 offset0:115 offset1:123
	ds_read2_b32 v[74:75], v63 offset0:148 offset1:156
	ds_read2_b32 v[76:77], v63 offset0:181 offset1:189
	ds_read2_b32 v[78:79], v63 offset0:214 offset1:222
	ds_read2_b32 v[82:83], v63 offset0:247 offset1:255
	v_lshl_add_u64 v[16:17], v[80:81], 0, v[0:1]
	v_or_b32_e32 v0, s8, v60
	v_lshlrev_b32_e32 v0, 10, v0
	global_store_dwordx4 v[16:17], v[12:15], off sc1
	v_lshl_add_u64 v[16:17], v[80:81], 0, v[0:1]
	v_or_b32_e32 v0, s8, v61
	s_waitcnt lgkmcnt(6)
	v_cvt_pk_bf16_f32 v12, v20, v18
	s_waitcnt lgkmcnt(4)
	v_cvt_pk_bf16_f32 v13, v22, v72
	s_waitcnt lgkmcnt(2)
	v_cvt_pk_bf16_f32 v14, v74, v76
	s_waitcnt lgkmcnt(0)
	v_cvt_pk_bf16_f32 v15, v78, v82
	v_lshlrev_b32_e32 v0, 10, v0
	global_store_dwordx4 v[16:17], v[12:15], off sc1
	v_lshl_add_u64 v[16:17], v[80:81], 0, v[0:1]
	s_nop 0
	v_cvt_pk_bf16_f32 v12, v21, v19
	v_cvt_pk_bf16_f32 v13, v23, v73
	v_cvt_pk_bf16_f32 v14, v75, v77
	v_cvt_pk_bf16_f32 v15, v79, v83
	global_store_dwordx4 v[16:17], v[12:15], off sc1
	s_waitcnt lgkmcnt(0)

; __device__ __forceinline__ void p0_prologue(const Ptrs& P, LAS unsigned char* lds, int vcu, int G) {
;     ...
;     for (int it = gw; it < NITEMS; it += NGW) {
;         int r = it;
;         if (r < I_IN) { p0_transpose_item<true>(P.w_in, 1024, NIN, (u16*)(P.ws + WS_WT), scr, r, lane); continue; } r -= I_IN;
;         if (r < I_A) { p0_transpose_item<false>(P.wa, 1024, 1024, (u16*)(P.ws + WS_WA), scr, r, lane); continue; } r -= I_A;
;         if (r < I_B) { p0_transpose_item<false>(P.wb, 512, 1024, (u16*)(P.ws + WS_WB), scr, r, lane); continue; } r -= I_B;
.LBB0_31:
	s_andn2_b64 vcc, exec, s[8:9]
	s_cbranch_vccnz .LBB0_33
; #define LAS __attribute__((address_space(3)))
; __device__ __forceinline__ unsigned pk_bf16(float lo, float hi) { typedef __bf16 b2 __attribute__((ext_vector_type(2))); f32x2 v = {lo, hi}; b2 b = __builtin_convertvector(v, b2); return __builtin_bit_cast(unsigned, b); }
; template <bool MAP> __device__ __forceinline__ void p0_transpose_item(const float* W, int K, int N, u16* WT, LAS float* scr, int item, int lane) {
;     const int nblk = N / 32, kb = item / nblk, nb = item % nblk, k0 = 64 * kb, n0 = 32 * nb;
;     float tv[32];
; #pragma unroll
;     for (int i = 0; i < 32; ++i) tv[i] = W[(size_t)(k0 + 2 * i + (lane >> 5)) * N + n0 + (lane & 31)];
; #pragma unroll
;     for (int i = 0; i < 32; ++i) scr[(2 * i + (lane >> 5)) * 33 + (lane & 31)] = tv[i];
;     asm volatile("s_waitcnt lgkmcnt(0)" ::: "memory");
;     const int c = lane & 7;
; #pragma unroll
;     for (int j = 0; j < 4; ++j) { const int n = (lane >> 3) + 8 * j; const LAS float* s = scr + (8 * c) * 33 + n;
;         u32x4 o; o.x = pk_bf16(s[0 * 33], s[1 * 33]); o.y = pk_bf16(s[2 * 33], s[3 * 33]); o.z = pk_bf16(s[4 * 33], s[5 * 33]); o.w = pk_bf16(s[6 * 33], s[7 * 33]);
;         const int r = MAP ? wt_row_of_col(n0 + n) : (n0 + n);
;         *(u32x4*)(WT + (size_t)r * K + k0 + 8 * c) = o; }
;     asm volatile("s_waitcnt lgkmcnt(0)" ::: "memory");
	s_add_i32 s8, s18, 0xfffd4000
	s_add_i32 s9, s21, 0xc80000
	s_and_b32 s8, s8, 0x3e0
	s_and_b32 s9, s9, 0xf0000
	s_or_b32 s9, s8, s9
	v_or_b32_e32 v0, s9, v26
	v_or_b32_e32 v14, s9, v29
	v_or_b32_e32 v15, s9, v30
	v_or_b32_e32 v16, s9, v31
	v_or_b32_e32 v17, s9, v32
	v_or_b32_e32 v18, s9, v33
	v_lshlrev_b32_e32 v0, 2, v0
	v_or_b32_e32 v12, s9, v27
	v_or_b32_e32 v13, s9, v28
	v_lshlrev_b32_e32 v14, 2, v14
	v_lshlrev_b32_e32 v15, 2, v15
	v_lshlrev_b32_e32 v16, 2, v16
	v_lshlrev_b32_e32 v17, 2, v17
	v_lshlrev_b32_e32 v18, 2, v18
	v_lshlrev_b32_e32 v12, 2, v12
	v_lshlrev_b32_e32 v13, 2, v13
	global_load_dword v19, v0, s[68:69] nt
	global_load_dword v20, v12, s[68:69] nt
	global_load_dword v21, v13, s[68:69] nt
	s_nop 0
	global_load_dword v14, v14, s[68:69] nt
	s_nop 0
	global_load_dword v15, v15, s[68:69] nt
	s_nop 0
	global_load_dword v16, v16, s[68:69] nt
	s_nop 0
	global_load_dword v17, v17, s[68:69] nt
	s_nop 0
	global_load_dword v18, v18, s[68:69] nt
	v_or_b32_e32 v0, s9, v34
	v_or_b32_e32 v22, s9, v37
	v_or_b32_e32 v23, s9, v38
	v_or_b32_e32 v71, s9, v39
	v_or_b32_e32 v72, s9, v40
	v_or_b32_e32 v73, s9, v41
	v_lshlrev_b32_e32 v0, 2, v0
	v_or_b32_e32 v12, s9, v35
	v_or_b32_e32 v13, s9, v36
	v_lshlrev_b32_e32 v22, 2, v22
	v_lshlrev_b32_e32 v23, 2, v23
	v_lshlrev_b32_e32 v71, 2, v71
	v_lshlrev_b32_e32 v72, 2, v72
	v_lshlrev_b32_e32 v73, 2, v73
	v_lshlrev_b32_e32 v12, 2, v12
	v_lshlrev_b32_e32 v13, 2, v13
	global_load_dword v74, v0, s[68:69] nt
	global_load_dword v75, v12, s[68:69] nt
	global_load_dword v76, v13, s[68:69] nt
	s_nop 0
	global_load_dword v22, v22, s[68:69] nt
	s_nop 0
	global_load_dword v23, v23, s[68:69] nt
	s_nop 0
	global_load_dword v71, v71, s[68:69] nt
	s_nop 0
	global_load_dword v72, v72, s[68:69] nt
	s_nop 0
	global_load_dword v73, v73, s[68:69] nt
	v_or_b32_e32 v0, s9, v42
	v_or_b32_e32 v77, s9, v45
	v_or_b32_e32 v78, s9, v46
	v_or_b32_e32 v79, s9, v47
	v_or_b32_e32 v80, s9, v48
	v_or_b32_e32 v81, s9, v49
	v_lshlrev_b32_e32 v0, 2, v0
	v_or_b32_e32 v12, s9, v43
	v_or_b32_e32 v13, s9, v44
	v_lshlrev_b32_e32 v77, 2, v77
	v_lshlrev_b32_e32 v78, 2, v78
	v_lshlrev_b32_e32 v79, 2, v79
	v_lshlrev_b32_e32 v80, 2, v80
	v_lshlrev_b32_e32 v81, 2, v81
	v_lshlrev_b32_e32 v12, 2, v12
	v_lshlrev_b32_e32 v13, 2, v13
	global_load_dword v82, v0, s[68:69] nt
	global_load_dword v83, v12, s[68:69] nt
	global_load_dword v84, v13, s[68:69] nt
	s_nop 0
	global_load_dword v77, v77, s[68:69] nt
	s_nop 0
	global_load_dword v78, v78, s[68:69] nt
	s_nop 0
	global_load_dword v79, v79, s[68:69] nt
	s_nop 0
	global_load_dword v80, v80, s[68:69] nt
	s_nop 0
	global_load_dword v81, v81, s[68:69] nt
	v_or_b32_e32 v0, s9, v50
	v_lshlrev_b32_e32 v85, 2, v0
	v_or_b32_e32 v0, s9, v51
	v_lshlrev_b32_e32 v86, 2, v0
	v_or_b32_e32 v0, s9, v52
	v_lshlrev_b32_e32 v87, 2, v0
	v_or_b32_e32 v0, s9, v53
	v_lshlrev_b32_e32 v88, 2, v0
	v_or_b32_e32 v0, s9, v54
	s_and_b32 s6, s26, 0x3e0
	v_lshlrev_b32_e32 v89, 2, v0
	v_or_b32_e32 v0, s9, v55
	v_lshlrev_b32_e32 v90, 2, v0
	v_or_b32_e32 v0, s9, v56
	s_add_i32 s6, s6, s21
	v_lshlrev_b32_e32 v91, 2, v0
	v_add_u32_e32 v0, s6, v26
	v_add_u32_e32 v0, 0x180000, v0
	v_or_b32_e32 v0, 0xf800, v0
	v_lshl_add_u64 v[12:13], v[0:1], 2, s[68:69]
	global_load_dword v0, v85, s[68:69] nt
	s_nop 0
	global_load_dword v85, v86, s[68:69] nt
	s_nop 0
	global_load_dword v86, v87, s[68:69] nt
	s_nop 0
	global_load_dword v87, v88, s[68:69] nt
	s_nop 0
	global_load_dword v88, v89, s[68:69] nt
	s_nop 0
	global_load_dword v89, v90, s[68:69] nt
	s_nop 0
	global_load_dword v90, v91, s[68:69] nt
	s_nop 0
	global_load_dword v12, v[12:13], off nt
	s_add_i32 s6, s23, 0x600
	s_and_b32 s6, s6, 0x3c0
	s_lshl_b32 s6, s6, 1
	s_waitcnt vmcnt(30)
	ds_write2_b32 v62, v19, v20 offset1:66
	s_waitcnt vmcnt(28)
	ds_write2_b32 v62, v21, v14 offset0:132 offset1:198
	s_waitcnt vmcnt(26)
	ds_write2_b32 v64, v15, v16 offset0:8 offset1:74
	s_waitcnt vmcnt(24)
	ds_write2_b32 v64, v17, v18 offset0:140 offset1:206
	s_waitcnt vmcnt(22)
	ds_write2_b32 v65, v74, v75 offset0:16 offset1:82
	s_waitcnt vmcnt(20)
	ds_write2_b32 v65, v76, v22 offset0:148 offset1:214
	s_waitcnt vmcnt(18)
	ds_write2_b32 v66, v23, v71 offset0:24 offset1:90
	s_waitcnt vmcnt(16)
	ds_write2_b32 v66, v72, v73 offset0:156 offset1:222
	s_waitcnt vmcnt(14)
	ds_write2_b32 v67, v82, v83 offset0:32 offset1:98
	s_waitcnt vmcnt(12)
	ds_write2_b32 v67, v84, v77 offset0:164 offset1:230
	s_waitcnt vmcnt(10)
	ds_write2_b32 v68, v78, v79 offset0:40 offset1:106
	s_waitcnt vmcnt(8)
	ds_write2_b32 v68, v80, v81 offset0:172 offset1:238
	s_waitcnt vmcnt(6)
	ds_write2_b32 v69, v0, v85 offset0:48 offset1:114
	s_waitcnt vmcnt(4)
	ds_write2_b32 v69, v86, v87 offset0:180 offset1:246
	s_waitcnt vmcnt(2)
	ds_write2_b32 v70, v88, v89 offset0:56 offset1:122
	s_waitcnt vmcnt(0)
	ds_write2_b32 v70, v90, v12 offset0:188 offset1:254
	s_waitcnt lgkmcnt(0)
	ds_read2_b32 v[16:17], v63 offset0:33 offset1:41
	ds_read2_b32 v[18:19], v63 offset1:8
	ds_read2_b32 v[20:21], v63 offset0:66 offset1:74
	ds_read2_b32 v[22:23], v63 offset0:99 offset1:107
	ds_read2_b32 v[72:73], v63 offset0:132 offset1:140
	ds_read2_b32 v[74:75], v63 offset0:165 offset1:173
	ds_read2_b32 v[76:77], v63 offset0:198 offset1:206
	ds_read2_b32 v[78:79], v63 offset0:231 offset1:239
	v_or_b32_e32 v0, s8, v58
	v_lshl_add_u64 v[80:81], v[10:11], 0, s[6:7]
	v_lshlrev_b32_e32 v0, 11, v0
	s_waitcnt lgkmcnt(6)
	v_cvt_pk_bf16_f32 v12, v18, v16
	s_waitcnt lgkmcnt(4)
	v_cvt_pk_bf16_f32 v13, v20, v22
	s_waitcnt lgkmcnt(2)
	v_cvt_pk_bf16_f32 v14, v72, v74
	s_waitcnt lgkmcnt(0)
	v_cvt_pk_bf16_f32 v15, v76, v78
	v_lshl_add_u64 v[82:83], v[80:81], 0, v[0:1]
	global_store_dwordx4 v[82:83], v[12:15], off sc1
	v_or_b32_e32 v0, s8, v59
	v_lshlrev_b32_e32 v0, 11, v0
	v_cvt_pk_bf16_f32 v12, v19, v17
	v_cvt_pk_bf16_f32 v13, v21, v23
	v_cvt_pk_bf16_f32 v14, v73, v75
	v_cvt_pk_bf16_f32 v15, v77, v79
	ds_read2_b32 v[18:19], v63 offset0:49 offset1:57
	ds_read2_b32 v[20:21], v63 offset0:16 offset1:24
	ds_read2_b32 v[22:23], v63 offset0:82 offset1:90
	ds_read2_b32 v[72:73], v63 offset0:115 offset1:123
	ds_read2_b32 v[74:75], v63 offset0:148 offset1:156
	ds_read2_b32 v[76:77], v63 offset0:181 offset1:189
	ds_read2_b32 v[78:79], v63 offset0:214 offset1:222
	ds_read2_b32 v[82:83], v63 offset0:247 offset1:255
	v_lshl_add_u64 v[16:17], v[80:81], 0, v[0:1]
	v_or_b32_e32 v0, s8, v60
	v_lshlrev_b32_e32 v0, 11, v0
	global_store_dwordx4 v[16:17], v[12:15], off sc1
	v_lshl_add_u64 v[16:17], v[80:81], 0, v[0:1]
	v_or_b32_e32 v0, s8, v61
	s_waitcnt lgkmcnt(6)
	v_cvt_pk_bf16_f32 v12, v20, v18
	s_waitcnt lgkmcnt(4)
	v_cvt_pk_bf16_f32 v13, v22, v72
	s_waitcnt lgkmcnt(2)
	v_cvt_pk_bf16_f32 v14, v74, v76
	s_waitcnt lgkmcnt(0)
	v_cvt_pk_bf16_f32 v15, v78, v82
	v_lshlrev_b32_e32 v0, 11, v0
	global_store_dwordx4 v[16:17], v[12:15], off sc1
	v_lshl_add_u64 v[16:17], v[80:81], 0, v[0:1]
	s_nop 0
	v_cvt_pk_bf16_f32 v12, v21, v19
	v_cvt_pk_bf16_f32 v13, v23, v73
	v_cvt_pk_bf16_f32 v14, v75, v77
	v_cvt_pk_bf16_f32 v15, v79, v83
	global_store_dwordx4 v[16:17], v[12:15], off sc1
	s_waitcnt lgkmcnt(0)

; __device__ __forceinline__ void p0_prologue(const Ptrs& P, LAS unsigned char* lds, int vcu, int G) {
;     ...
;     for (int m = gw; m < TT; m += 2 * NGW) {
;         const int m2 = (m + NGW < TT) ? m + NGW : m;
;         const f32x4* xr = (const f32x4*)(P.x + (size_t)m * DM) + lane; const f32x4* xr2 = (const f32x4*)(P.x + (size_t)m2 * DM) + lane; f32x4 v[4], v2[4]; float s = 0.f, s2 = 0.f;
; #pragma unroll
;         for (int j = 0; j < 4; ++j) { v[j] = xr[64 * j]; v2[j] = xr2[64 * j]; }
; #pragma unroll
;         for (int j = 0; j < 4; ++j) { s += (v[j].x * v[j].x + v[j].y * v[j].y) + (v[j].z * v[j].z + v[j].w * v[j].w); s2 += (v2[j].x * v2[j].x + v2[j].y * v2[j].y) + (v2[j].z * v2[j].z + v2[j].w * v2[j].w); }
;         const float rstd = rsqrtf(wave_sum(s) * (1.0f / DM) + NORM_EPS), rstd2 = rsqrtf(wave_sum(s2) * (1.0f / DM) + NORM_EPS);
.LBB0_57:
	s_add_i32 s8, s0, s17
	s_cmpk_lt_i32 s8, 0x4000
	s_cselect_b32 s10, s8, s0
	s_ashr_i32 s1, s0, 31
	s_lshl_b64 s[12:13], s[0:1], 12
	s_ashr_i32 s11, s10, 31
	v_lshl_add_u64 v[22:23], v[2:3], 0, s[12:13]
	global_load_dwordx4 v[14:17], v[4:5], off nt
	s_lshl_b64 s[12:13], s[10:11], 12
	global_load_dwordx4 v[18:21], v[22:23], off nt
	global_load_dwordx4 v[26:29], v[22:23], off offset:1024 nt
	global_load_dwordx4 v[30:33], v[22:23], off offset:3072 nt
	global_load_dwordx4 v[34:37], v[22:23], off offset:2048 nt
	v_lshl_add_u64 v[22:23], v[2:3], 0, s[12:13]
	global_load_dwordx4 v[38:41], v[22:23], off nt
	global_load_dwordx4 v[42:45], v[22:23], off offset:1024 nt
	global_load_dwordx4 v[46:49], v[22:23], off offset:3072 nt
	global_load_dwordx4 v[50:53], v[22:23], off offset:2048 nt
	s_lshl_b64 s[0:1], s[0:1], 11
	v_lshl_add_u64 v[54:55], v[0:1], 0, s[0:1]
	s_lshl_b64 s[0:1], s[10:11], 11
	v_lshl_add_u64 v[56:57], v[0:1], 0, s[0:1]
	s_waitcnt vmcnt(7)
	v_pk_mul_f32 v[22:23], v[20:21], v[20:21]
	v_pk_mul_f32 v[58:59], v[18:19], v[18:19]
	s_waitcnt vmcnt(6)
	v_pk_mul_f32 v[60:61], v[28:29], v[28:29]
	v_pk_mul_f32 v[62:63], v[26:27], v[26:27]
	s_waitcnt vmcnt(4)
	v_mul_f32_e32 v64, v35, v35
	v_mul_f32_e32 v66, v37, v37
	v_pk_mov_b32 v[68:69], v[58:59], v[22:23] op_sel:[1,0]
	v_mov_b32_e32 v59, v23
	s_waitcnt vmcnt(3)
	v_pk_mul_f32 v[22:23], v[40:41], v[40:41]
	v_pk_mul_f32 v[70:71], v[38:39], v[38:39]
	v_pk_mov_b32 v[72:73], v[62:63], v[60:61] op_sel:[1,0]
	v_mov_b32_e32 v63, v61
	s_waitcnt vmcnt(2)
	v_pk_mul_f32 v[60:61], v[44:45], v[44:45]
	v_pk_mul_f32 v[74:75], v[42:43], v[42:43]
	v_mul_f32_e32 v77, v32, v32
	v_mul_f32_e32 v79, v33, v33
	v_pk_fma_f32 v[64:65], v[34:35], v[34:35], v[64:65] op_sel_hi:[1,1,0]
	v_pk_fma_f32 v[66:67], v[36:37], v[36:37], v[66:67] op_sel_hi:[1,1,0]
	v_pk_add_f32 v[58:59], v[68:69], v[58:59]
	v_pk_mov_b32 v[68:69], v[70:71], v[22:23] op_sel:[1,0]
	v_mov_b32_e32 v71, v23
	v_pk_add_f32 v[22:23], v[72:73], v[62:63]
	v_pk_mov_b32 v[62:63], v[74:75], v[60:61] op_sel:[1,0]
	v_mov_b32_e32 v75, v61
	s_waitcnt vmcnt(0)
	v_mul_f32_e32 v76, v51, v51
	v_mul_f32_e32 v78, v53, v53
	v_mov_b32_e32 v65, v77
	v_mov_b32_e32 v67, v79
	v_pk_add_f32 v[68:69], v[68:69], v[70:71]
	v_pk_add_f32 v[62:63], v[62:63], v[74:75]
	v_mul_f32_e32 v13, v30, v30
	v_mul_f32_e32 v25, v31, v31
	v_mul_f32_e32 v80, v46, v46
	v_mul_f32_e32 v81, v47, v47
	v_mul_f32_e32 v82, v48, v48
	v_mul_f32_e32 v83, v49, v49
	v_pk_fma_f32 v[60:61], v[50:51], v[50:51], v[76:77] op_sel_hi:[1,1,0]
	v_pk_fma_f32 v[72:73], v[52:53], v[52:53], v[78:79] op_sel_hi:[1,1,0]
	v_pk_add_f32 v[58:59], v[58:59], v[58:59] op_sel:[0,1] op_sel_hi:[1,0]
	v_pk_add_f32 v[22:23], v[22:23], v[22:23] op_sel:[0,1] op_sel_hi:[1,0]
	v_pk_add_f32 v[64:65], v[64:65], v[66:67]
	v_pk_add_f32 v[66:67], v[68:69], v[68:69] op_sel:[0,1] op_sel_hi:[1,0]
	v_pk_add_f32 v[62:63], v[62:63], v[62:63] op_sel:[0,1] op_sel_hi:[1,0]
	v_mov_b32_e32 v61, v82
	v_mov_b32_e32 v73, v83
	v_mov_b32_e32 v59, v13
	v_mov_b32_e32 v23, v25
	v_mov_b32_e32 v67, v80
	v_mov_b32_e32 v63, v81
	v_pk_add_f32 v[60:61], v[60:61], v[72:73]
	v_pk_add_f32 v[22:23], v[58:59], v[22:23]
	v_pk_add_f32 v[58:59], v[66:67], v[62:63]
	v_pk_add_f32 v[22:23], v[22:23], v[64:65]
	v_pk_add_f32 v[58:59], v[58:59], v[60:61]
	v_mov_b32_e32 v61, v22
	v_mov_b32_e32 v60, v58
	v_mov_b32_e32 v22, v59
	v_pk_add_f32 v[22:23], v[60:61], v[22:23]
	ds_bpermute_b32 v59, v7, v23
	ds_bpermute_b32 v58, v7, v22
	s_waitcnt lgkmcnt(0)
	v_pk_add_f32 v[22:23], v[22:23], v[58:59]
	ds_bpermute_b32 v59, v8, v23
	ds_bpermute_b32 v58, v8, v22
	s_waitcnt lgkmcnt(0)
	v_pk_add_f32 v[22:23], v[22:23], v[58:59]
	ds_bpermute_b32 v59, v9, v23
	ds_bpermute_b32 v58, v9, v22
	s_waitcnt lgkmcnt(0)
	v_pk_add_f32 v[22:23], v[22:23], v[58:59]
	ds_bpermute_b32 v59, v10, v23
	ds_bpermute_b32 v58, v10, v22
	s_waitcnt lgkmcnt(0)
; __device__ __forceinline__ unsigned pk_bf16(float lo, float hi) { typedef __bf16 b2 __attribute__((ext_vector_type(2))); f32x2 v = {lo, hi}; b2 b = __builtin_convertvector(v, b2); return __builtin_bit_cast(unsigned, b); }
; __device__ __forceinline__ void p0_prologue(const Ptrs& P, LAS unsigned char* lds, int vcu, int G) {
;     ...
;         const float rstd = rsqrtf(wave_sum(s) * (1.0f / DM) + NORM_EPS), rstd2 = rsqrtf(wave_sum(s2) * (1.0f / DM) + NORM_EPS);
;         u32x2* o8 = (u32x2*)(H + (size_t)m * DM) + lane; u32x2* o82 = (u32x2*)(H + (size_t)m2 * DM) + lane;
; #pragma unroll
;         for (int j = 0; j < 4; ++j) { const f32x4 w4 = ((const f32x4*)P.norm_w)[lane + 64 * j];
;             o8[64 * j] = (u32x2){pk_bf16(v[j].x * rstd * w4.x, v[j].y * rstd * w4.y), pk_bf16(v[j].z * rstd * w4.z, v[j].w * rstd * w4.w)};
;             o82[64 * j] = (u32x2){pk_bf16(v2[j].x * rstd2 * w4.x, v2[j].y * rstd2 * w4.y), pk_bf16(v2[j].z * rstd2 * w4.z, v2[j].w * rstd2 * w4.w)}; }
	v_pk_add_f32 v[22:23], v[22:23], v[58:59]
	ds_bpermute_b32 v59, v11, v23
	ds_bpermute_b32 v58, v11, v22
	s_waitcnt lgkmcnt(0)
	v_pk_add_f32 v[22:23], v[22:23], v[58:59]
	ds_bpermute_b32 v59, v12, v23
	ds_bpermute_b32 v58, v12, v22
	s_waitcnt lgkmcnt(0)
	v_pk_add_f32 v[22:23], v[22:23], v[58:59]
	s_nop 0
	v_pk_fma_f32 v[22:23], v[22:23], s[6:7], v[6:7] op_sel_hi:[1,0,0]
	s_nop 0
	v_mul_f32_e32 v13, 0x4b800000, v23
	v_cmp_gt_f32_e64 s[0:1], s7, v23
	v_mul_f32_e32 v25, 0x4b800000, v22
	v_cmp_gt_f32_e32 vcc, s7, v22
	v_cndmask_b32_e64 v13, v23, v13, s[0:1]
	v_rsq_f32_e32 v13, v13
	v_cndmask_b32_e32 v22, v22, v25, vcc
	v_rsq_f32_e32 v23, v22
	v_mul_f32_e32 v22, 0x45800000, v13
	v_cndmask_b32_e64 v22, v13, v22, s[0:1]
	v_mul_f32_e32 v25, 0x45800000, v23
	v_cndmask_b32_e32 v58, v23, v25, vcc
	v_pk_mul_f32 v[18:19], v[18:19], v[22:23] op_sel_hi:[1,0]
	v_pk_mul_f32 v[20:21], v[20:21], v[22:23] op_sel_hi:[1,0]
	v_pk_mul_f32 v[38:39], v[38:39], v[58:59] op_sel_hi:[1,0]
	v_pk_mul_f32 v[40:41], v[40:41], v[58:59] op_sel_hi:[1,0]
	v_pk_mul_f32 v[18:19], v[14:15], v[18:19]
	v_pk_mul_f32 v[20:21], v[16:17], v[20:21]
	v_pk_mul_f32 v[14:15], v[14:15], v[38:39]
	v_pk_mul_f32 v[16:17], v[16:17], v[40:41]
	v_cvt_pk_bf16_f32 v18, v18, v19
	v_cvt_pk_bf16_f32 v19, v20, v21
	v_cvt_pk_bf16_f32 v14, v14, v15
	v_cvt_pk_bf16_f32 v15, v16, v17
	global_store_dwordx2 v[54:55], v[18:19], off sc1
	global_store_dwordx2 v[56:57], v[14:15], off sc1
	global_load_dwordx4 v[14:17], v[4:5], off offset:1024 nt
	v_pk_mul_f32 v[18:19], v[26:27], v[22:23] op_sel_hi:[1,0]
	v_pk_mul_f32 v[20:21], v[28:29], v[22:23] op_sel_hi:[1,0]
	v_pk_mul_f32 v[26:27], v[42:43], v[58:59] op_sel_hi:[1,0]
	v_pk_mul_f32 v[28:29], v[44:45], v[58:59] op_sel_hi:[1,0]
	s_add_i32 s0, s8, s17
	s_cmpk_gt_i32 s0, 0x3fff
	s_waitcnt vmcnt(0)
	v_pk_mul_f32 v[18:19], v[14:15], v[18:19]
	v_pk_mul_f32 v[20:21], v[16:17], v[20:21]
	v_pk_mul_f32 v[14:15], v[14:15], v[26:27]
	v_pk_mul_f32 v[16:17], v[16:17], v[28:29]
	v_cvt_pk_bf16_f32 v18, v18, v19
	v_cvt_pk_bf16_f32 v19, v20, v21
	v_cvt_pk_bf16_f32 v14, v14, v15
	v_cvt_pk_bf16_f32 v15, v16, v17
	global_store_dwordx2 v[54:55], v[18:19], off offset:512 sc1
	global_store_dwordx2 v[56:57], v[14:15], off offset:512 sc1
	global_load_dwordx4 v[14:17], v[4:5], off offset:2048 nt
	v_pk_mul_f32 v[18:19], v[34:35], v[22:23] op_sel_hi:[1,0]
	v_pk_mul_f32 v[20:21], v[36:37], v[22:23] op_sel_hi:[1,0]
	v_pk_mul_f32 v[26:27], v[50:51], v[58:59] op_sel_hi:[1,0]
	v_pk_mul_f32 v[28:29], v[52:53], v[58:59] op_sel_hi:[1,0]
	s_waitcnt vmcnt(0)
	v_pk_mul_f32 v[18:19], v[18:19], v[14:15]
	v_pk_mul_f32 v[20:21], v[20:21], v[16:17]
	v_pk_mul_f32 v[14:15], v[14:15], v[26:27]
	v_pk_mul_f32 v[16:17], v[16:17], v[28:29]
	v_cvt_pk_bf16_f32 v18, v18, v19
	v_cvt_pk_bf16_f32 v19, v20, v21
	v_cvt_pk_bf16_f32 v14, v14, v15
	v_cvt_pk_bf16_f32 v15, v16, v17
	global_store_dwordx2 v[54:55], v[18:19], off offset:1024 sc1
	global_store_dwordx2 v[56:57], v[14:15], off offset:1024 sc1
	global_load_dwordx4 v[14:17], v[4:5], off offset:3072 nt
	v_pk_mul_f32 v[18:19], v[30:31], v[22:23] op_sel_hi:[1,0]
	v_pk_mul_f32 v[20:21], v[32:33], v[22:23] op_sel_hi:[1,0]
	v_pk_mul_f32 v[22:23], v[46:47], v[58:59] op_sel_hi:[1,0]
	v_pk_mul_f32 v[26:27], v[48:49], v[58:59] op_sel_hi:[1,0]
	s_waitcnt vmcnt(0)
	v_pk_mul_f32 v[18:19], v[18:19], v[14:15]
	v_pk_mul_f32 v[20:21], v[20:21], v[16:17]
	v_pk_mul_f32 v[14:15], v[22:23], v[14:15]
	v_pk_mul_f32 v[16:17], v[26:27], v[16:17]
	v_cvt_pk_bf16_f32 v18, v18, v19
	v_cvt_pk_bf16_f32 v19, v20, v21
	v_cvt_pk_bf16_f32 v14, v14, v15
	v_cvt_pk_bf16_f32 v15, v16, v17
	global_store_dwordx2 v[54:55], v[18:19], off offset:1536 sc1
	global_store_dwordx2 v[56:57], v[14:15], off offset:1536 sc1
	s_cbranch_scc0 .LBB0_57

; __device__ __forceinline__ void p0_prologue(const Ptrs& P, LAS unsigned char* lds, int vcu, int G) {
;     ...
;     float* cosT = (float*)(P.ws + WS_COS); float* sinT = (float*)(P.ws + WS_SIN);
;     for (int e = (vcu * 512 + tid); e < TT * 32; e += G * 512) {
;         const int row = e >> 5, j = e & 31;
;         const float inv = exp2f(-(float)j * (13.287712379549449f / 32.0f));
;         const float ang = (float)P.pos[row] * inv;
;         const double rev = (double)ang * 0.15915494309189535; const float fr = (float)(rev - __builtin_rint(rev));
;         cosT[e] = __builtin_amdgcn_cosf(fr); sinT[e] = __builtin_amdgcn_sinf(fr);
;     }
.LBB0_60:
	v_ashrrev_i32_e32 v6, 5, v0
	v_ashrrev_i32_e32 v7, 31, v6
	s_waitcnt lgkmcnt(0)
	v_lshl_add_u64 v[6:7], v[6:7], 2, s[58:59]
	global_load_dword v1, v[6:7], off nt
	v_add_co_u32_e32 v6, vcc, 0x200000, v2
	v_add_u32_e32 v0, s6, v0
	s_nop 0
	v_addc_co_u32_e32 v7, vcc, 0, v3, vcc
	v_cmp_lt_i32_e32 vcc, s7, v0
	s_or_b64 s[10:11], vcc, s[10:11]
	s_waitcnt vmcnt(0)
	v_cvt_f32_i32_e32 v1, v1
	v_mul_f32_e32 v1, v4, v1
	v_cvt_f64_f32_e32 v[8:9], v1
	v_mul_f64 v[10:11], v[8:9], s[12:13]
	v_rndne_f64_e32 v[10:11], v[10:11]
	v_fma_f64 v[8:9], v[8:9], s[12:13], -v[10:11]
	v_cvt_f32_f64_e32 v1, v[8:9]
	v_cos_f32_e32 v5, v1
	v_sin_f32_e32 v1, v1
	global_store_dword v[2:3], v5, off sc1
	global_store_dword v[6:7], v1, off sc1
	v_lshl_add_u64 v[2:3], v[2:3], 0, s[8:9]
	s_andn2_b64 exec, exec, s[10:11]
	s_cbranch_execnz .LBB0_60
